# v13 plus P2 queue split changed from 3/8 to 2/8 of workgroups starting on the sample-attention queue
# baseline (speedup 1.0000x reference)
; __device__ __forceinline__ void p2_run_b(Frame& F) {
;     if (!(F.item_mask & 8)) return;
;     const int t = p2_fetch(F, CW_TICKET);
;     if (t < N_ATTP) (void)attn_prompt_loop(F, t);
; }
; __device__ __forceinline__ void p2_phase(Frame& F) {
;     ...
;     if (F.item_mask & 64) {
;         if ((int)blockIdx.x < 16) { for (int i = (int)blockIdx.x; i < N_ATTS; i += 16) attn_sample_item(F, i >> 3, i & 7); }
;         return;
;     }
;     ...
;     if (F.item_mask & 1) { const int tg = p2_fetch(F, CW_TICKET_G); if (tg < N_GLAP) gla_prompt_item(F, tg >> 2, tg & 3); }
;     if ((((int)blockIdx.x >> 3) & 7) < 3) { p2_run_a(F); p2_run_b(F); } else { p2_run_b(F); p2_run_a(F); }
.LBB0_604:
	s_and_b32 s0, s2, 56
	s_cmp_gt_u32 s0, 15
	s_mov_b64 s[4:5], -1
	s_cbranch_scc0 .LBB0_854
	s_bitcmp0_b32 s62, 3
	s_cbranch_scc1 .LBB0_774
	v_cmp_eq_u32_e32 vcc, 0, v0
	s_and_saveexec_b64 s[4:5], vcc
	s_cbranch_execz .LBB0_610
	s_mov_b64 s[8:9], exec
	v_mbcnt_lo_u32_b32 v1, s8, 0
	v_mbcnt_hi_u32_b32 v1, s9, v1
	v_cmp_eq_u32_e32 vcc, 0, v1
	s_and_saveexec_b64 s[6:7], vcc
	s_cbranch_execz .LBB0_609
	s_bcnt1_i32_b64 s0, s[8:9]
	s_waitcnt vmcnt(0) lgkmcnt(0)
	v_mov_b32_e32 v2, 0
	v_mov_b32_e32 v3, s0
	global_atomic_add v2, v2, v3, s[58:59] offset:256 sc0
